# dense: waves 4-7 take the barrier that ends their matrix phase before their last PV block (waves 0-3 run their matrix-phase head under it)
# speedup vs baseline: 1.0075x; 1.0075x over previous
; #define SBAR() __builtin_amdgcn_sched_barrier(0)
; #define KRD(f, d0, kb) asm volatile("ds_read_b128 %0, %2 offset:%3\n\tds_read_b128 %1, %2 offset:%4" : "=&v"(f.a), "=&v"(f.b) : "v"((kb) + koff[(d0) & 3]), "i"(((d0) >> 2) * 128), "i"(((d0) >> 2) * 128 + 8192) : "memory")
; #define QMM(f, d0) do { pA0 = __builtin_amdgcn_mfma_f32_32x32x16_bf16(f.a, qr[d0], pA0, 0, 0, 0); pA1 = __builtin_amdgcn_mfma_f32_32x32x16_bf16(f.b, qr[d0], pA1, 0, 0, 0); } while (0)
; #define LW(n) do { asm volatile("s_waitcnt lgkmcnt(" #n ")" ::: "memory"); SBAR(); } while (0)
; #define PP_BAR(VM) do { if (VM) { asm volatile("s_waitcnt vmcnt(4) lgkmcnt(0)\n\ts_barrier" ::: "memory"); } else { asm volatile("s_waitcnt vmcnt(0) lgkmcnt(0)\n\ts_barrier" ::: "memory"); } } while (0)
; #define PP_BAR_PLAIN() asm volatile("s_waitcnt lgkmcnt(0)\n\ts_barrier" ::: "memory")
;     ...
;         LW(10); QMM(k1_, 1); SBAR(); KRD(k1_, 3, kb_);
;         LW(4);  pv_mm(o[0], fa_, pa0, pa1, pa2, pa3); SBAR(); pv_rd<1>(fb_, vb_);
;         LW(10); QMM(k0_, 2); SBAR(); KRD(k0_, 4, kb_);
;         LW(10); QMM(k1_, 3); SBAR(); KRD(k1_, 5, kb_);
;         LW(4);  pv_mm(o[1], fb_, pa0, pa1, pa2, pa3); SBAR(); pv_rd<2>(fa_, vb_);
;         LW(10); QMM(k0_, 4); SBAR(); KRD(k0_, 6, kb_);
;         LW(10); QMM(k1_, 5); SBAR(); KRD(k1_, 7, kb_);
;         LW(4);  pv_mm(o[2], fa_, pa0, pa1, pa2, pa3); SBAR(); pv_rd<3>(fb_, vb_);
;         LW(10); QMM(k0_, 6); SBAR();
;         LW(8);  QMM(k1_, 7); SBAR();
;         LW(0);  pv_mm(o[3], fb_, pa0, pa1, pa2, pa3);
;       } else pv_d0(o, VBUF(t), pa0, pa1, pa2, pa3);
;       if (t + 1 < NT) { if (grpB) PP_BAR(t + 3 < NT); else PP_BAR_PLAIN(); }
.LBB0_69:
	s_waitcnt lgkmcnt(10)
	v_mfma_f32_32x32x16_bf16 v[98:113], v[82:85], v[158:161], v[66:81]
	v_mfma_f32_32x32x16_bf16 v[82:97], v[202:205], v[158:161], v[66:81]
	v_add_u32_e32 v217, s87, v237
	ds_read_b128 v[202:205], v217 offset:0
	ds_read_b128 v[250:253], v217 offset:0x2000
	s_waitcnt lgkmcnt(10)
	v_mfma_f32_32x32x16_bf16 v[98:113], v[198:201], v[154:157], v[98:113]
	v_mfma_f32_32x32x16_bf16 v[82:97], v[194:197], v[154:157], v[82:97]
	v_add_u32_e32 v206, s87, v236
	ds_read_b128 v[194:197], v206 offset:0
	ds_read_b128 v[198:201], v206 offset:0x2000
	s_waitcnt lgkmcnt(4)
	v_mfma_f32_32x32x16_bf16 v[2:17], v[174:177], v[190:193], v[2:17]
	ds_read_b64_tr_b16 v[190:191], v246 offset:0x3200
	ds_read_b64_tr_b16 v[192:193], v246 offset:0x3a00
	v_mfma_f32_32x32x16_bf16 v[2:17], v[170:173], v[186:189], v[2:17]
	ds_read_b64_tr_b16 v[186:187], v246 offset:0x2200
	ds_read_b64_tr_b16 v[188:189], v246 offset:0x2a00
	v_mfma_f32_32x32x16_bf16 v[2:17], v[166:169], v[182:185], v[2:17]
	ds_read_b64_tr_b16 v[182:183], v246 offset:0x1200
	ds_read_b64_tr_b16 v[184:185], v246 offset:0x1a00
	v_mfma_f32_32x32x16_bf16 v[2:17], v[162:165], v[178:181], v[2:17]
	ds_read_b64_tr_b16 v[178:179], v246 offset:0x200
	ds_read_b64_tr_b16 v[180:181], v246 offset:0xa00
	s_waitcnt lgkmcnt(10)
	v_mfma_f32_32x32x16_bf16 v[98:113], v[202:205], v[150:153], v[98:113]
	v_mfma_f32_32x32x16_bf16 v[82:97], v[250:253], v[150:153], v[82:97]
	ds_read_b128 v[202:205], v248 offset:0x80
	ds_read_b128 v[250:253], v248 offset:0x2080
	s_waitcnt lgkmcnt(10)
	v_mfma_f32_32x32x16_bf16 v[98:113], v[194:197], v[146:149], v[98:113]
	v_mfma_f32_32x32x16_bf16 v[82:97], v[198:201], v[146:149], v[82:97]
	ds_read_b128 v[194:197], v247 offset:0x80
	ds_read_b128 v[198:201], v247 offset:0x2080
	s_waitcnt lgkmcnt(4)
	v_mfma_f32_32x32x16_bf16 v[50:65], v[174:177], v[178:181], v[50:65]
	ds_read_b64_tr_b16 v[178:179], v246 offset:0x400
	ds_read_b64_tr_b16 v[180:181], v246 offset:0xc00
	v_mfma_f32_32x32x16_bf16 v[50:65], v[170:173], v[182:185], v[50:65]
	ds_read_b64_tr_b16 v[182:183], v246 offset:0x1400
	ds_read_b64_tr_b16 v[184:185], v246 offset:0x1c00
	v_mfma_f32_32x32x16_bf16 v[50:65], v[166:169], v[186:189], v[50:65]
	ds_read_b64_tr_b16 v[186:187], v246 offset:0x2400
	ds_read_b64_tr_b16 v[188:189], v246 offset:0x2c00
	v_mfma_f32_32x32x16_bf16 v[50:65], v[162:165], v[190:193], v[50:65]
	ds_read_b64_tr_b16 v[190:191], v246 offset:0x3400
	ds_read_b64_tr_b16 v[192:193], v246 offset:0x3c00
	s_waitcnt lgkmcnt(10)
	v_mfma_f32_32x32x16_bf16 v[98:113], v[202:205], v[142:145], v[98:113]
	v_mfma_f32_32x32x16_bf16 v[82:97], v[250:253], v[142:145], v[82:97]
	ds_read_b128 v[202:205], v217 offset:0x80
	ds_read_b128 v[248:251], v217 offset:0x2080
	s_waitcnt lgkmcnt(10)
	v_mfma_f32_32x32x16_bf16 v[98:113], v[194:197], v[138:141], v[98:113]
	v_mfma_f32_32x32x16_bf16 v[82:97], v[198:201], v[138:141], v[82:97]
	ds_read_b128 v[194:197], v206 offset:0x80
	ds_read_b128 v[198:201], v206 offset:0x2080
	s_waitcnt lgkmcnt(4)
	v_mfma_f32_32x32x16_bf16 v[34:49], v[174:177], v[178:181], v[34:49]
	ds_read_b64_tr_b16 v[178:179], v246 offset:0x600
	ds_read_b64_tr_b16 v[180:181], v246 offset:0xe00
	v_mfma_f32_32x32x16_bf16 v[34:49], v[170:173], v[182:185], v[34:49]
	ds_read_b64_tr_b16 v[182:183], v246 offset:0x1600
	ds_read_b64_tr_b16 v[184:185], v246 offset:0x1e00
	v_mfma_f32_32x32x16_bf16 v[34:49], v[166:169], v[186:189], v[34:49]
	ds_read_b64_tr_b16 v[186:187], v246 offset:0x2600
	ds_read_b64_tr_b16 v[188:189], v246 offset:0x2e00
	v_mfma_f32_32x32x16_bf16 v[34:49], v[162:165], v[190:193], v[34:49]
	ds_read_b64_tr_b16 v[190:191], v246 offset:0x3600
	ds_read_b64_tr_b16 v[192:193], v246 offset:0x3e00
	s_waitcnt lgkmcnt(10)
	v_mfma_f32_32x32x16_bf16 v[98:113], v[202:205], v[134:137], v[98:113]
	v_mfma_f32_32x32x16_bf16 v[82:97], v[248:251], v[134:137], v[82:97]
	s_waitcnt lgkmcnt(8)
	v_mfma_f32_32x32x16_bf16 v[98:113], v[194:197], v[130:133], v[98:113]
	v_mfma_f32_32x32x16_bf16 v[82:97], v[198:201], v[130:133], v[82:97]
	s_and_b64 vcc, exec, s[0:1]
	s_cbranch_vccz .Leb_b
	s_waitcnt lgkmcnt(0)
	v_mfma_f32_32x32x16_bf16 v[18:33], v[174:177], v[178:181], v[18:33]
	v_mfma_f32_32x32x16_bf16 v[18:33], v[170:173], v[182:185], v[18:33]
	v_mfma_f32_32x32x16_bf16 v[18:33], v[166:169], v[186:189], v[18:33]
	v_mfma_f32_32x32x16_bf16 v[18:33], v[162:165], v[190:193], v[18:33]
	s_waitcnt lgkmcnt(0)
	s_barrier
.Leb_join:
	v_add_f32_e32 v190, v243, v245
	s_cmp_eq_u32 s84, 0x1f4000
	v_fmac_f32_e32 v190, v241, v242
	s_cbranch_scc1 .LBB0_76

; #define LW(n) do { asm volatile("s_waitcnt lgkmcnt(" #n ")" ::: "memory"); SBAR(); } while (0)
; #define PP_BAR(VM) do { if (VM) { asm volatile("s_waitcnt vmcnt(4) lgkmcnt(0)\n\ts_barrier" ::: "memory"); } else { asm volatile("s_waitcnt vmcnt(0) lgkmcnt(0)\n\ts_barrier" ::: "memory"); } } while (0)
; #define PP_BAR_PLAIN() asm volatile("s_waitcnt lgkmcnt(0)\n\ts_barrier" ::: "memory")
;     ...
;         LW(0);  pv_mm(o[3], fb_, pa0, pa1, pa2, pa3);
;       } else pv_d0(o, VBUF(t), pa0, pa1, pa2, pa3);
;       if (t + 1 < NT) { if (grpB) PP_BAR(t + 3 < NT); else PP_BAR_PLAIN(); }
.Leb_b:
	s_waitcnt vmcnt(4) lgkmcnt(0)
	s_barrier
	v_mfma_f32_32x32x16_bf16 v[18:33], v[174:177], v[178:181], v[18:33]
	v_mfma_f32_32x32x16_bf16 v[18:33], v[170:173], v[182:185], v[18:33]
	v_mfma_f32_32x32x16_bf16 v[18:33], v[166:169], v[186:189], v[18:33]
	v_mfma_f32_32x32x16_bf16 v[18:33], v[162:165], v[190:193], v[18:33]
	s_branch .Leb_join
